# vres columns: K-split across 8 waves with LDS reduction (448 KB per CU instead of 1.5 MB); in-proj 44 tiles all layers; rstd pipelining; PRM overlap
# speedup vs baseline: 1.0045x; 1.0045x over previous
; #define LAS __attribute__((address_space(3)))
;     DI void init(const bf16* A_, int lda, const bf16* B_, int ldb, int nM, int nN, int K, int G_, int c_) { T.init(nM, nN); G = G_; c = c_; nt = K / BK; A = (const char*)A_; B = (const char*)B_; ta = (size_t)BM * lda * 2; tb = (size_t)BM * ldb * 2; }
;     DI void init(const bf16* A_, int lda, const bf16* B_, int ldb, int nM, int nN, int G_, int c_) { T.init(nM, nN); G = G_; c = c_; A = (const char*)A_; B = (const char*)B_; ta = (size_t)BM * lda * 2; tb = (size_t)BM * ldb * 2; }
; #define SEAM(k) do { if (IN((k) + 1) && IN(k)) xcd_barrier(bar); } while (0)
; #define FRAME() const CAS Args* ap; const Frame F = make_frame(lds, ap, wv); const CAS Args& A = *ap; (void)A
; __global__ void __launch_bounds__(512, 2) trunk_fwd(Args args_unused) {
;     ...
;         if (PHEN(1) && IN(s0 + 1)) { FRAME();
;             const int nN = (l == 0) ? 44 : 45;
;             const LAS float* rs = rstd_table(F);
;             SchedPlain S; S.init((const bf16*)F.out, XP, (const bf16*)lw(F, l, LW_WIN), D, M / BM, nN, D, F.G, F.bid);
;             EpiInproj E{(bf16*)(F.ws + WS_R2), A.in[3] + (size_t)l * 6144, (bf16*)(F.ws + WS_ZS5), rs};
;             gemm_phase<EpiInproj, SchedPlain>(F.lds, F.wave, XP, D, S, E);
;             SEAM(s0 + 1);
.LBB0_489:
	s_cmp_eq_u32 s71, 0
	s_cbranch_scc1 .Lvres_done
	s_load_dwordx4 s[4:7], s[88:89], 0x130
	v_mbcnt_lo_u32_b32 v238, -1, 0
	v_mbcnt_hi_u32_b32 v238, -1, v238
	v_readlane_b32 s0, v252, 0
	v_and_b32_e32 v239, 15, v238
	v_lshrrev_b32_e32 v240, 4, v238
	s_lshl_b32 s0, s0, 6
	s_and_b32 s1, s90, 3
	s_lshl_b32 s1, s1, 4
	s_add_i32 s1, s0, s1
	v_add_u32_e32 v184, s1, v239
	v_lshlrev_b32_e32 v241, 7, v184
	v_mul_u32_u24_e32 v242, 0x5a00, v184
	v_lshl_add_u32 v242, v240, 3, v242
	v_add_u32_e32 v243, s0, v239
	v_lshlrev_b32_e32 v243, 12, v243
	v_lshl_add_u32 v243, v240, 4, v243
	s_lshl_b32 s2, s90, 9
	v_add_u32_e32 v243, s2, v243
	v_add_u32_e32 v244, 0x10000, v243
	v_add_u32_e32 v245, 0x20000, v243
	v_add_u32_e32 v246, 0x30000, v243
	v_lshlrev_b32_e32 v247, 12, v239
	v_lshl_add_u32 v247, v240, 4, v247
	v_add_u32_e32 v247, s2, v247
	v_add_u32_e32 v248, 0x10000, v247
	v_add_u32_e32 v249, 0x20000, v247
	s_mul_i32 s17, s71, 0x7eca000
	s_waitcnt lgkmcnt(0)
	s_add_u32 s100, s6, 0x49c28000
	s_addc_u32 s101, s7, 0
	global_load_dwordx4 v[196:199], v241, s[100:101] offset:32
	global_load_dwordx4 v[200:203], v241, s[100:101] offset:48
	global_load_dwordx4 v[204:207], v241, s[100:101]
	global_load_dwordx4 v[208:211], v241, s[100:101] offset:16
	global_load_dwordx4 v[212:215], v241, s[100:101] offset:96
	global_load_dwordx4 v[216:219], v241, s[100:101] offset:112
	global_load_dwordx4 v[220:223], v241, s[100:101] offset:64
	global_load_dwordx4 v[234:237], v241, s[100:101] offset:80
	s_add_u32 s0, s6, s17
	s_addc_u32 s1, s7, 0
	s_add_u32 s0, s0, 0x2d00000
	s_addc_u32 s1, s1, 0
	s_add_u32 s16, s6, 0x23c2d800
	s_addc_u32 s17, s7, 0
	global_load_dwordx4 v[0:3], v243, s[4:5]
	global_load_dwordx4 v[4:7], v244, s[4:5]
	global_load_dwordx4 v[8:11], v245, s[4:5]
	global_load_dwordx4 v[12:15], v246, s[4:5]
	global_load_dwordx4 v[16:19], v247, s[0:1]
	global_load_dwordx4 v[20:23], v248, s[0:1]
	global_load_dwordx4 v[24:27], v249, s[0:1]
	global_load_dwordx4 v[28:31], v243, s[4:5] offset:64
	global_load_dwordx4 v[32:35], v244, s[4:5] offset:64
	global_load_dwordx4 v[36:39], v245, s[4:5] offset:64
	global_load_dwordx4 v[40:43], v246, s[4:5] offset:64
	global_load_dwordx4 v[44:47], v247, s[0:1] offset:64
	global_load_dwordx4 v[48:51], v248, s[0:1] offset:64
	global_load_dwordx4 v[52:55], v249, s[0:1] offset:64
	global_load_dwordx4 v[56:59], v243, s[4:5] offset:128
	global_load_dwordx4 v[60:63], v244, s[4:5] offset:128
	global_load_dwordx4 v[64:67], v245, s[4:5] offset:128
	global_load_dwordx4 v[68:71], v246, s[4:5] offset:128
	global_load_dwordx4 v[72:75], v247, s[0:1] offset:128
	global_load_dwordx4 v[76:79], v248, s[0:1] offset:128
	global_load_dwordx4 v[80:83], v249, s[0:1] offset:128
	global_load_dwordx4 v[84:87], v243, s[4:5] offset:192
	global_load_dwordx4 v[88:91], v244, s[4:5] offset:192
	global_load_dwordx4 v[92:95], v245, s[4:5] offset:192
	global_load_dwordx4 v[96:99], v246, s[4:5] offset:192
	global_load_dwordx4 v[100:103], v247, s[0:1] offset:192
	global_load_dwordx4 v[104:107], v248, s[0:1] offset:192
	global_load_dwordx4 v[108:111], v249, s[0:1] offset:192
	global_load_dwordx4 v[112:115], v243, s[4:5] offset:256
	global_load_dwordx4 v[116:119], v244, s[4:5] offset:256
	global_load_dwordx4 v[120:123], v245, s[4:5] offset:256
	global_load_dwordx4 v[124:127], v246, s[4:5] offset:256
	global_load_dwordx4 v[128:131], v247, s[0:1] offset:256
	global_load_dwordx4 v[132:135], v248, s[0:1] offset:256
	global_load_dwordx4 v[136:139], v249, s[0:1] offset:256
	s_waitcnt vmcnt(28)
	v_mfma_f32_16x16x32_bf16 v[140:143], v[16:19], v[0:3], 0
	v_mfma_f32_16x16x32_bf16 v[144:147], v[20:23], v[0:3], 0
	v_mfma_f32_16x16x32_bf16 v[148:151], v[24:27], v[0:3], 0
	v_mfma_f32_16x16x32_bf16 v[152:155], v[16:19], v[4:7], 0
	v_mfma_f32_16x16x32_bf16 v[156:159], v[20:23], v[4:7], 0
	v_mfma_f32_16x16x32_bf16 v[160:163], v[24:27], v[4:7], 0
	v_mfma_f32_16x16x32_bf16 v[164:167], v[16:19], v[8:11], 0
	v_mfma_f32_16x16x32_bf16 v[168:171], v[20:23], v[8:11], 0
	v_mfma_f32_16x16x32_bf16 v[172:175], v[24:27], v[8:11], 0
	v_mfma_f32_16x16x32_bf16 v[176:179], v[16:19], v[12:15], 0
	v_mfma_f32_16x16x32_bf16 v[180:183], v[20:23], v[12:15], 0
	v_mfma_f32_16x16x32_bf16 v[188:191], v[24:27], v[12:15], 0
	global_load_dwordx4 v[0:3], v243, s[4:5] offset:320
	global_load_dwordx4 v[4:7], v244, s[4:5] offset:320
	global_load_dwordx4 v[8:11], v245, s[4:5] offset:320
	global_load_dwordx4 v[12:15], v246, s[4:5] offset:320
	global_load_dwordx4 v[16:19], v247, s[0:1] offset:320
	global_load_dwordx4 v[20:23], v248, s[0:1] offset:320
	global_load_dwordx4 v[24:27], v249, s[0:1] offset:320
	s_waitcnt vmcnt(28)
	v_mfma_f32_16x16x32_bf16 v[140:143], v[44:47], v[28:31], v[140:143]
	v_mfma_f32_16x16x32_bf16 v[144:147], v[48:51], v[28:31], v[144:147]
	v_mfma_f32_16x16x32_bf16 v[148:151], v[52:55], v[28:31], v[148:151]
	v_mfma_f32_16x16x32_bf16 v[152:155], v[44:47], v[32:35], v[152:155]
	v_mfma_f32_16x16x32_bf16 v[156:159], v[48:51], v[32:35], v[156:159]
	v_mfma_f32_16x16x32_bf16 v[160:163], v[52:55], v[32:35], v[160:163]
	v_mfma_f32_16x16x32_bf16 v[164:167], v[44:47], v[36:39], v[164:167]
	v_mfma_f32_16x16x32_bf16 v[168:171], v[48:51], v[36:39], v[168:171]
	v_mfma_f32_16x16x32_bf16 v[172:175], v[52:55], v[36:39], v[172:175]
	v_mfma_f32_16x16x32_bf16 v[176:179], v[44:47], v[40:43], v[176:179]
	v_mfma_f32_16x16x32_bf16 v[180:183], v[48:51], v[40:43], v[180:183]
	v_mfma_f32_16x16x32_bf16 v[188:191], v[52:55], v[40:43], v[188:191]
	global_load_dwordx4 v[28:31], v243, s[4:5] offset:384
	global_load_dwordx4 v[32:35], v244, s[4:5] offset:384
	global_load_dwordx4 v[36:39], v245, s[4:5] offset:384
	global_load_dwordx4 v[40:43], v246, s[4:5] offset:384
	global_load_dwordx4 v[44:47], v247, s[0:1] offset:384
	global_load_dwordx4 v[48:51], v248, s[0:1] offset:384
	global_load_dwordx4 v[52:55], v249, s[0:1] offset:384
	s_waitcnt vmcnt(28)
; #define LAS __attribute__((address_space(3)))
;     DI void init(const bf16* A_, int lda, const bf16* B_, int ldb, int nM, int nN, int K, int G_, int c_) { T.init(nM, nN); G = G_; c = c_; nt = K / BK; A = (const char*)A_; B = (const char*)B_; ta = (size_t)BM * lda * 2; tb = (size_t)BM * ldb * 2; }
;     DI void init(const bf16* A_, int lda, const bf16* B_, int ldb, int nM, int nN, int G_, int c_) { T.init(nM, nN); G = G_; c = c_; A = (const char*)A_; B = (const char*)B_; ta = (size_t)BM * lda * 2; tb = (size_t)BM * ldb * 2; }
; #define SEAM(k) do { if (IN((k) + 1) && IN(k)) xcd_barrier(bar); } while (0)
; #define FRAME() const CAS Args* ap; const Frame F = make_frame(lds, ap, wv); const CAS Args& A = *ap; (void)A
; __global__ void __launch_bounds__(512, 2) trunk_fwd(Args args_unused) {
;     ...
;         if (PHEN(1) && IN(s0 + 1)) { FRAME();
;             const int nN = (l == 0) ? 44 : 45;
;             const LAS float* rs = rstd_table(F);
;             SchedPlain S; S.init((const bf16*)F.out, XP, (const bf16*)lw(F, l, LW_WIN), D, M / BM, nN, D, F.G, F.bid);
;             EpiInproj E{(bf16*)(F.ws + WS_R2), A.in[3] + (size_t)l * 6144, (bf16*)(F.ws + WS_ZS5), rs};
;             gemm_phase<EpiInproj, SchedPlain>(F.lds, F.wave, XP, D, S, E);
;             SEAM(s0 + 1);
	v_mfma_f32_16x16x32_bf16 v[140:143], v[72:75], v[56:59], v[140:143]
	v_mfma_f32_16x16x32_bf16 v[144:147], v[76:79], v[56:59], v[144:147]
	v_mfma_f32_16x16x32_bf16 v[148:151], v[80:83], v[56:59], v[148:151]
	v_mfma_f32_16x16x32_bf16 v[152:155], v[72:75], v[60:63], v[152:155]
	v_mfma_f32_16x16x32_bf16 v[156:159], v[76:79], v[60:63], v[156:159]
	v_mfma_f32_16x16x32_bf16 v[160:163], v[80:83], v[60:63], v[160:163]
	v_mfma_f32_16x16x32_bf16 v[164:167], v[72:75], v[64:67], v[164:167]
	v_mfma_f32_16x16x32_bf16 v[168:171], v[76:79], v[64:67], v[168:171]
	v_mfma_f32_16x16x32_bf16 v[172:175], v[80:83], v[64:67], v[172:175]
	v_mfma_f32_16x16x32_bf16 v[176:179], v[72:75], v[68:71], v[176:179]
	v_mfma_f32_16x16x32_bf16 v[180:183], v[76:79], v[68:71], v[180:183]
	v_mfma_f32_16x16x32_bf16 v[188:191], v[80:83], v[68:71], v[188:191]
	global_load_dwordx4 v[56:59], v243, s[4:5] offset:448
	global_load_dwordx4 v[60:63], v244, s[4:5] offset:448
	global_load_dwordx4 v[64:67], v245, s[4:5] offset:448
	global_load_dwordx4 v[68:71], v246, s[4:5] offset:448
	global_load_dwordx4 v[72:75], v247, s[0:1] offset:448
	global_load_dwordx4 v[76:79], v248, s[0:1] offset:448
	global_load_dwordx4 v[80:83], v249, s[0:1] offset:448
	s_waitcnt vmcnt(28)
	v_mfma_f32_16x16x32_bf16 v[140:143], v[100:103], v[84:87], v[140:143]
	v_mfma_f32_16x16x32_bf16 v[144:147], v[104:107], v[84:87], v[144:147]
	v_mfma_f32_16x16x32_bf16 v[148:151], v[108:111], v[84:87], v[148:151]
	v_mfma_f32_16x16x32_bf16 v[152:155], v[100:103], v[88:91], v[152:155]
	v_mfma_f32_16x16x32_bf16 v[156:159], v[104:107], v[88:91], v[156:159]
	v_mfma_f32_16x16x32_bf16 v[160:163], v[108:111], v[88:91], v[160:163]
	v_mfma_f32_16x16x32_bf16 v[164:167], v[100:103], v[92:95], v[164:167]
	v_mfma_f32_16x16x32_bf16 v[168:171], v[104:107], v[92:95], v[168:171]
	v_mfma_f32_16x16x32_bf16 v[172:175], v[108:111], v[92:95], v[172:175]
	v_mfma_f32_16x16x32_bf16 v[176:179], v[100:103], v[96:99], v[176:179]
	v_mfma_f32_16x16x32_bf16 v[180:183], v[104:107], v[96:99], v[180:183]
	v_mfma_f32_16x16x32_bf16 v[188:191], v[108:111], v[96:99], v[188:191]
	s_waitcnt vmcnt(21)
	v_mfma_f32_16x16x32_bf16 v[140:143], v[128:131], v[112:115], v[140:143]
	v_mfma_f32_16x16x32_bf16 v[144:147], v[132:135], v[112:115], v[144:147]
	v_mfma_f32_16x16x32_bf16 v[148:151], v[136:139], v[112:115], v[148:151]
	v_mfma_f32_16x16x32_bf16 v[152:155], v[128:131], v[116:119], v[152:155]
	v_mfma_f32_16x16x32_bf16 v[156:159], v[132:135], v[116:119], v[156:159]
	v_mfma_f32_16x16x32_bf16 v[160:163], v[136:139], v[116:119], v[160:163]
	v_mfma_f32_16x16x32_bf16 v[164:167], v[128:131], v[120:123], v[164:167]
	v_mfma_f32_16x16x32_bf16 v[168:171], v[132:135], v[120:123], v[168:171]
	v_mfma_f32_16x16x32_bf16 v[172:175], v[136:139], v[120:123], v[172:175]
	v_mfma_f32_16x16x32_bf16 v[176:179], v[128:131], v[124:127], v[176:179]
	v_mfma_f32_16x16x32_bf16 v[180:183], v[132:135], v[124:127], v[180:183]
	v_mfma_f32_16x16x32_bf16 v[188:191], v[136:139], v[124:127], v[188:191]
	s_waitcnt vmcnt(14)
	v_mfma_f32_16x16x32_bf16 v[140:143], v[16:19], v[0:3], v[140:143]
	v_mfma_f32_16x16x32_bf16 v[144:147], v[20:23], v[0:3], v[144:147]
	v_mfma_f32_16x16x32_bf16 v[148:151], v[24:27], v[0:3], v[148:151]
	v_mfma_f32_16x16x32_bf16 v[152:155], v[16:19], v[4:7], v[152:155]
	v_mfma_f32_16x16x32_bf16 v[156:159], v[20:23], v[4:7], v[156:159]
	v_mfma_f32_16x16x32_bf16 v[160:163], v[24:27], v[4:7], v[160:163]
	v_mfma_f32_16x16x32_bf16 v[164:167], v[16:19], v[8:11], v[164:167]
	v_mfma_f32_16x16x32_bf16 v[168:171], v[20:23], v[8:11], v[168:171]
	v_mfma_f32_16x16x32_bf16 v[172:175], v[24:27], v[8:11], v[172:175]
	v_mfma_f32_16x16x32_bf16 v[176:179], v[16:19], v[12:15], v[176:179]
	v_mfma_f32_16x16x32_bf16 v[180:183], v[20:23], v[12:15], v[180:183]
	v_mfma_f32_16x16x32_bf16 v[188:191], v[24:27], v[12:15], v[188:191]
	s_waitcnt vmcnt(7)
	v_mfma_f32_16x16x32_bf16 v[140:143], v[44:47], v[28:31], v[140:143]
	v_mfma_f32_16x16x32_bf16 v[144:147], v[48:51], v[28:31], v[144:147]
	v_mfma_f32_16x16x32_bf16 v[148:151], v[52:55], v[28:31], v[148:151]
	v_mfma_f32_16x16x32_bf16 v[152:155], v[44:47], v[32:35], v[152:155]
	v_mfma_f32_16x16x32_bf16 v[156:159], v[48:51], v[32:35], v[156:159]
	v_mfma_f32_16x16x32_bf16 v[160:163], v[52:55], v[32:35], v[160:163]
	v_mfma_f32_16x16x32_bf16 v[164:167], v[44:47], v[36:39], v[164:167]
	v_mfma_f32_16x16x32_bf16 v[168:171], v[48:51], v[36:39], v[168:171]
	v_mfma_f32_16x16x32_bf16 v[172:175], v[52:55], v[36:39], v[172:175]
	v_mfma_f32_16x16x32_bf16 v[176:179], v[44:47], v[40:43], v[176:179]
	v_mfma_f32_16x16x32_bf16 v[180:183], v[48:51], v[40:43], v[180:183]
	v_mfma_f32_16x16x32_bf16 v[188:191], v[52:55], v[40:43], v[188:191]
	s_waitcnt vmcnt(0)
	v_mfma_f32_16x16x32_bf16 v[140:143], v[72:75], v[56:59], v[140:143]
	v_mfma_f32_16x16x32_bf16 v[144:147], v[76:79], v[56:59], v[144:147]
	v_mfma_f32_16x16x32_bf16 v[148:151], v[80:83], v[56:59], v[148:151]
	v_mfma_f32_16x16x32_bf16 v[152:155], v[72:75], v[60:63], v[152:155]
	v_mfma_f32_16x16x32_bf16 v[156:159], v[76:79], v[60:63], v[156:159]
	v_mfma_f32_16x16x32_bf16 v[160:163], v[80:83], v[60:63], v[160:163]
	v_mfma_f32_16x16x32_bf16 v[164:167], v[72:75], v[64:67], v[164:167]
	v_mfma_f32_16x16x32_bf16 v[168:171], v[76:79], v[64:67], v[168:171]
	v_mfma_f32_16x16x32_bf16 v[172:175], v[80:83], v[64:67], v[172:175]
	v_mfma_f32_16x16x32_bf16 v[176:179], v[72:75], v[68:71], v[176:179]
	v_mfma_f32_16x16x32_bf16 v[180:183], v[76:79], v[68:71], v[180:183]
	v_mfma_f32_16x16x32_bf16 v[188:191], v[80:83], v[68:71], v[188:191]
	v_lshlrev_b32_e32 v0, 4, v238
	s_lshl_b32 s2, s90, 10
	v_add_u32_e32 v1, s2, v0
	v_add_u32_e32 v2, 0xc000, v1
	s_nop 15
	s_nop 15
	ds_write_b128 v1, v[140:143]
	ds_write_b128 v1, v[144:147] offset:8192
	ds_write_b128 v1, v[148:151] offset:16384
	ds_write_b128 v1, v[152:155] offset:24576
	ds_write_b128 v1, v[156:159] offset:32768
	ds_write_b128 v1, v[160:163] offset:40960
	ds_write_b128 v2, v[164:167]
	ds_write_b128 v2, v[168:171] offset:8192
	ds_write_b128 v2, v[172:175] offset:16384
	ds_write_b128 v2, v[176:179] offset:24576
	ds_write_b128 v2, v[180:183] offset:32768
	ds_write_b128 v2, v[188:191] offset:40960
	s_waitcnt lgkmcnt(0)
	s_barrier
; #define GAS __attribute__((address_space(1)))
; DI unsigned pk2(float lo, float hi) { f32x2 v = {lo, hi}; bf16x2_t r = __builtin_convertvector(v, bf16x2_t); return __builtin_bit_cast(unsigned, r); }
; DI float sigmoidf_(float x) { return __builtin_amdgcn_rcpf(1.f + __expf(-x)); }
;     DI bool operator()(AccT& acc, const Unit& u, int wr, int wc, int fr, int fq) const {
;     ...
;                     f32x4 v0 = acc[ai][bj][m][0] * rsv[ai][m], v1 = acc[ai][bj][m][1] * rsv[ai][m];
;                     if (gate) { v0 += b0; v1 += b1;
; #pragma unroll
;                         for (int e = 0; e < 4; ++e) { v0[e] = sigmoidf_(v0[e]); v1[e] = sigmoidf_(v1[e]); } }
;                     u32x4 w; w.x = pk2(v0[0], v0[1]); w.y = pk2(v0[2], v0[3]); w.z = pk2(v1[0], v1[1]); w.w = pk2(v1[2], v1[3]);
;                     if (s5c) *(GAS u32x4*)(ZS5 + ((size_t)(col >> 4) * M + (row0 + ai * HALF + m * 16)) * 16 + (col & 8)) = w;
;                     else *(GAS u32x4*)(Z + (size_t)(row0 + ai * HALF + m * 16) * ZP + col) = w;
; DI const LAS float* rstd_table(const Frame& F) {
;     ...
;         f32x4 t = (p[0] + p[1]) + (p[2] + p[3]) + ((p[4] + p[5]) + (p[6] + p[7]));
;         tab[r] = 1.f / sqrtf(((t[0] + t[1]) + (t[2] + t[3])) * (1.f / D) + NORM_EPS);
	s_and_b32 s2, s90, 3
	s_mul_i32 s2, s2, 3
	s_lshr_b32 s3, s90, 2
	s_add_i32 s98, s2, s3
	s_add_i32 s99, s2, 2
	s_lshl_b32 s98, s98, 13
	s_lshl_b32 s99, s99, 13
	v_add_u32_e32 v3, s98, v0
	v_add_u32_e32 v4, s99, v0
	ds_read_b128 v[8:11], v3
	ds_read_b128 v[12:15], v3 offset:1024
	ds_read_b128 v[16:19], v3 offset:2048
	ds_read_b128 v[20:23], v3 offset:3072
	ds_read_b128 v[24:27], v3 offset:4096
	ds_read_b128 v[28:31], v3 offset:5120
	ds_read_b128 v[32:35], v3 offset:6144
	ds_read_b128 v[36:39], v3 offset:7168
	ds_read_b128 v[40:43], v4
	ds_read_b128 v[44:47], v4 offset:1024
	ds_read_b128 v[48:51], v4 offset:2048
	ds_read_b128 v[52:55], v4 offset:3072
	ds_read_b128 v[56:59], v4 offset:4096
	ds_read_b128 v[60:63], v4 offset:5120
	ds_read_b128 v[64:67], v4 offset:6144
	ds_read_b128 v[68:71], v4 offset:7168
	v_pk_add_f32 v[206:207], v[206:207], v[210:211]
	v_pk_add_f32 v[204:205], v[204:205], v[208:209]
	v_pk_add_f32 v[198:199], v[198:199], v[202:203]
	v_pk_add_f32 v[196:197], v[196:197], v[200:201]
	v_pk_add_f32 v[198:199], v[206:207], v[198:199]
	v_pk_add_f32 v[196:197], v[204:205], v[196:197]
	v_pk_add_f32 v[200:201], v[222:223], v[236:237]
	v_pk_add_f32 v[202:203], v[220:221], v[234:235]
	v_pk_add_f32 v[204:205], v[214:215], v[218:219]
	v_pk_add_f32 v[206:207], v[212:213], v[216:217]
	v_pk_add_f32 v[200:201], v[200:201], v[204:205]
	v_pk_add_f32 v[202:203], v[202:203], v[206:207]
	v_pk_add_f32 v[198:199], v[198:199], v[200:201]
	v_pk_add_f32 v[196:197], v[196:197], v[202:203]
	s_nop 0
	v_pk_mov_b32 v[200:201], v[196:197], v[198:199] op_sel:[1,0]
	v_mov_b32_e32 v197, v199
	v_pk_add_f32 v[196:197], v[200:201], v[196:197]
	s_nop 0
	v_add_f32_e32 v196, v196, v197
	v_fmamk_f32 v196, v196, 0x3a000000, v225
	v_mul_f32_e32 v197, 0x4f800000, v196
	v_cmp_gt_f32_e32 vcc, 0xf800000, v196
	s_nop 1
	v_cndmask_b32_e32 v196, v196, v197, vcc
	v_sqrt_f32_e32 v197, v196
	s_nop 0
	v_add_u32_e32 v198, -1, v197
	v_fma_f32 v199, -v198, v197, v196
	v_cmp_ge_f32_e64 s[100:101], 0, v199
	v_add_u32_e32 v199, 1, v197
	s_nop 0
	v_cndmask_b32_e64 v198, v197, v198, s[100:101]
	v_fma_f32 v197, -v199, v197, v196
	v_cmp_lt_f32_e64 s[100:101], 0, v197
	s_nop 1
	v_cndmask_b32_e64 v197, v198, v199, s[100:101]
	v_mul_f32_e32 v198, 0x37800000, v197
	v_cndmask_b32_e32 v197, v197, v198, vcc
	v_cmp_class_f32_e32 vcc, v196, v226
	s_nop 1
	v_cndmask_b32_e32 v196, v197, v196, vcc
	v_div_scale_f32 v197, s[100:101], v196, v196, 1.0
	v_rcp_f32_e32 v198, v197
	s_nop 0
	v_fma_f32 v199, -v197, v198, 1.0
	v_fmac_f32_e32 v198, v199, v198
	v_div_scale_f32 v199, vcc, 1.0, v196, 1.0
	v_mul_f32_e32 v200, v199, v198
	v_fma_f32 v201, -v197, v200, v199
	v_fmac_f32_e32 v200, v201, v198
	v_fma_f32 v197, -v197, v200, v199
	v_div_fmas_f32 v197, v197, v198, v200
	v_div_fixup_f32 v196, v197, v196, 1.0
	s_waitcnt lgkmcnt(0)
	v_pk_add_f32 v[8:9], v[8:9], v[12:13]
	v_pk_add_f32 v[10:11], v[10:11], v[14:15]
	v_pk_add_f32 v[16:17], v[16:17], v[20:21]
	v_pk_add_f32 v[18:19], v[18:19], v[22:23]
	v_pk_add_f32 v[24:25], v[24:25], v[28:29]
	v_pk_add_f32 v[26:27], v[26:27], v[30:31]
	v_pk_add_f32 v[32:33], v[32:33], v[36:37]
	v_pk_add_f32 v[34:35], v[34:35], v[38:39]
	v_pk_add_f32 v[8:9], v[8:9], v[16:17]
	v_pk_add_f32 v[10:11], v[10:11], v[18:19]
	v_pk_add_f32 v[24:25], v[24:25], v[32:33]
	v_pk_add_f32 v[26:27], v[26:27], v[34:35]
	v_pk_add_f32 v[8:9], v[8:9], v[24:25]
	v_pk_add_f32 v[10:11], v[10:11], v[26:27]
	v_pk_add_f32 v[40:41], v[40:41], v[44:45]
	v_pk_add_f32 v[42:43], v[42:43], v[46:47]
	v_pk_add_f32 v[48:49], v[48:49], v[52:53]
	v_pk_add_f32 v[50:51], v[50:51], v[54:55]
	v_pk_add_f32 v[56:57], v[56:57], v[60:61]
	v_pk_add_f32 v[58:59], v[58:59], v[62:63]
	v_pk_add_f32 v[64:65], v[64:65], v[68:69]
	v_pk_add_f32 v[66:67], v[66:67], v[70:71]
	v_pk_add_f32 v[40:41], v[40:41], v[48:49]
	v_pk_add_f32 v[42:43], v[42:43], v[50:51]
	v_pk_add_f32 v[56:57], v[56:57], v[64:65]
	v_pk_add_f32 v[58:59], v[58:59], v[66:67]
	v_pk_add_f32 v[40:41], v[40:41], v[56:57]
	v_pk_add_f32 v[42:43], v[42:43], v[58:59]
	v_mul_f32_e32 v8, v8, v196
	v_mul_f32_e32 v9, v9, v196
	v_mul_f32_e32 v10, v10, v196
	v_mul_f32_e32 v11, v11, v196
	v_mul_f32_e32 v40, v40, v196
	v_mul_f32_e32 v41, v41, v196
	v_mul_f32_e32 v42, v42, v196
	v_mul_f32_e32 v43, v43, v196
	v_cvt_pk_bf16_f32 v8, v8, v9
	v_cvt_pk_bf16_f32 v9, v10, v11
	v_cvt_pk_bf16_f32 v40, v40, v41
	v_cvt_pk_bf16_f32 v41, v42, v43
	s_lshl_b32 s3, s3, 5
	v_add_u32_e32 v5, s3, v242
	global_store_dwordx2 v5, v[8:9], s[16:17]
	global_store_dwordx2 v242, v[40:41], s[16:17] offset:64
